# code placement: the four GEMM K-loop heads padded (s_nop) to 64-byte boundaries
# baseline (speedup 1.0000x reference)
; #define PG8_STAGE(bufoff, gbase, voff) do { _Pragma("unroll") for (int _i = 0; _i < 2; ++_i) \
;         __builtin_amdgcn_global_load_lds((const unsigned*)((const char*)(gbase) + (voff)[_i]), (LAS unsigned*)(lds + (bufoff) + ldsw + _i * 8192), 16, 0, 0); } while (0)
; #define PG8_LDA(dst, b, h) do { _Pragma("unroll") for (int m = 0; m < 4; ++m) _Pragma("unroll") for (int k = 0; k < 2; ++k) dst[m][k] = *(const LAS bf16x8*)(lds + PG8_SA(b, h) + aoff + m * 2048 + k * 1024); } while (0)
; #define PG8_LDB(dst, b, h) do { _Pragma("unroll") for (int n = 0; n < 2; ++n) _Pragma("unroll") for (int k = 0; k < 2; ++k) dst[n][k] = *(const LAS bf16x8*)(lds + PG8_SB(b, h) + boff + n * 2048 + k * 1024); } while (0)
; #define PG8_MMA(ai, bj, At, Bt) do { __builtin_amdgcn_s_setprio(1); _Pragma("unroll") for (int m = 0; m < 4; ++m) _Pragma("unroll") for (int n = 0; n < 2; ++n) _Pragma("unroll") for (int k = 0; k < 2; ++k) \
;         acc[ai][bj][m][n] = __builtin_amdgcn_mfma_f32_16x16x32_bf16(Bt[n][k], At[m][k], acc[ai][bj][m][n], 0, 0, 0); __builtin_amdgcn_s_setprio(0); } while (0)
; #define PG8_WAIT_L(n) asm volatile("s_waitcnt lgkmcnt(" #n ")" ::: "memory")
; template <class Epi, bool AFTER = false>
; __device__ __forceinline__ void gemm_phase(LAS unsigned char* lds, const Gemm g, const StaticOrder& S, const Epi& E) {
;     ...
;         const bool has_next = S.next(ui + 1, nxt);
;         const char* nA = has_next ? (const char*)g.A + (size_t)nxt.pm * tstep : cA; const char* nB = has_next ? (const char*)g.Bt + (size_t)nxt.pn * tstep : cB;
;         for (int t = 0; t < nt; t += 2) {
;             const bool last = (t == nt - 2);
;             const char* a1 = cA + (size_t)(t + 1) * kstep;
;             const char* a2 = last ? nA : cA + (size_t)(t + 2) * kstep; const char* b2 = last ? nB : cB + (size_t)(t + 2) * kstep;
;             const char* a3 = a2 + kstep; const char* b3 = b2 + kstep;
;             PG8_LDB(B0, 0, 0); PG8_SCHED; PG8_LDA(At, 0, 0); PG8_STAGE(PG8_SA(1, 1), a1 + hstep, voffA);
;             PG8_WAIT_L(8); PG8_BAR; PG8_WAIT_L(0); PG8_MMA(0, 0, At, B0); PG8_BAR; PG8_SCHED;
;             PG8_LDB(B1, 0, 1); PG8_STAGE(PG8_SB(0, 0), b2, voffB);
;             PG8_BAR; PG8_WAIT_L(0); PG8_MMA(0, 1, At, B1); PG8_BAR;
;             PG8_LDA(At, 0, 1); PG8_STAGE(PG8_SA(0, 0), a2, voffA);
;             PG8_BAR; PG8_WAIT_L(0); PG8_MMA(1, 0, At, B0); PG8_BAR; PG8_SCHED;
.LBB0_419:
	s_ashr_i32 s17, s16, 31
	v_cmp_lt_i64_e32 vcc, s[18:19], v[144:145]
	s_lshl_b64 s[18:19], s[16:17], 19
	s_add_u32 s18, s74, s18
	s_addc_u32 s19, s75, s19
	s_and_b64 s[20:21], vcc, exec
	s_cselect_b32 s5, s19, s23
	s_cselect_b32 s7, s18, s22
	s_ashr_i32 s15, s14, 31
	s_lshl_b64 s[20:21], s[14:15], 19
	s_add_u32 s20, s40, s20
	s_addc_u32 s21, s41, s21
	s_and_b64 s[26:27], vcc, exec
	s_cselect_b32 s8, s21, s25
	s_cselect_b32 s15, s20, s24
	s_add_u32 s22, s22, 0x40080
	s_addc_u32 s23, s23, 0
	s_add_u32 s17, s24, 0x100
	s_addc_u32 s28, s25, 0
	s_mov_b32 s29, -2
	ds_read_b128 v[158:161], v151
	ds_read_b128 v[162:165], v151 offset:1024
	ds_read_b128 v[166:169], v151 offset:2048
	ds_read_b128 v[170:173], v151 offset:3072
	s_add_u32 s24, s22, 0xfffc0080
	s_addc_u32 s25, s23, -1
	s_cmp_eq_u32 s29, 12
	s_cselect_b32 s27, s5, s25
	s_cselect_b32 s26, s7, s24
	s_cselect_b32 s25, s8, s28
	s_cselect_b32 s24, s15, s17
	v_lshl_add_u64 v[148:149], s[22:23], 0, v[140:141]
	s_add_i32 m0, s43, 0xc000
	ds_read_b128 v[174:177], v152
	ds_read_b128 v[178:181], v152 offset:1024
	ds_read_b128 v[182:185], v152 offset:2048
	ds_read_b128 v[186:189], v152 offset:3072
	ds_read_b128 v[192:195], v152 offset:4096
	ds_read_b128 v[196:199], v152 offset:5120
	ds_read_b128 v[200:203], v152 offset:6144
	ds_read_b128 v[204:207], v152 offset:7168
	global_load_lds_dwordx4 v[148:149], off
	v_lshl_add_u64 v[148:149], s[22:23], 0, v[142:143]
	s_add_i32 m0, s43, 0xe000
	s_nop 0
	global_load_lds_dwordx4 v[148:149], off
	s_waitcnt lgkmcnt(8)
	s_barrier
	s_waitcnt lgkmcnt(0)
	s_setprio 1
	s_waitcnt lgkmcnt(0)
	v_mfma_f32_16x16x32_bf16 v[124:127], v[158:161], v[174:177], 0
	v_mfma_f32_16x16x32_bf16 v[120:123], v[166:169], v[174:177], 0
	v_mfma_f32_16x16x32_bf16 v[108:111], v[158:161], v[182:185], 0
	v_mfma_f32_16x16x32_bf16 v[104:107], v[166:169], v[182:185], 0
	v_mfma_f32_16x16x32_bf16 v[92:95], v[158:161], v[192:195], 0
	v_mfma_f32_16x16x32_bf16 v[88:91], v[166:169], v[192:195], 0
	v_mfma_f32_16x16x32_bf16 v[76:79], v[158:161], v[200:203], 0
	v_mfma_f32_16x16x32_bf16 v[72:75], v[166:169], v[200:203], 0
	v_mfma_f32_16x16x32_bf16 v[124:127], v[162:165], v[178:181], v[124:127]
	v_mfma_f32_16x16x32_bf16 v[120:123], v[170:173], v[178:181], v[120:123]
	v_mfma_f32_16x16x32_bf16 v[108:111], v[162:165], v[186:189], v[108:111]
	v_mfma_f32_16x16x32_bf16 v[104:107], v[170:173], v[186:189], v[104:107]
	v_mfma_f32_16x16x32_bf16 v[92:95], v[162:165], v[196:199], v[92:95]
	v_mfma_f32_16x16x32_bf16 v[88:91], v[170:173], v[196:199], v[88:91]
	v_mfma_f32_16x16x32_bf16 v[76:79], v[162:165], v[204:207], v[76:79]
	v_mfma_f32_16x16x32_bf16 v[72:75], v[170:173], v[204:207], v[72:75]
	s_setprio 0
	s_barrier
	s_add_i32 s30, s58, s42
	v_lshl_add_u64 v[148:149], s[24:25], 0, v[130:131]
	s_mov_b32 m0, s30
	ds_read_b128 v[208:211], v153
	ds_read_b128 v[214:217], v153 offset:1024
	ds_read_b128 v[218:221], v153 offset:2048
	ds_read_b128 v[222:225], v153 offset:3072
	global_load_lds_dwordx4 v[148:149], off
	v_lshl_add_u64 v[226:227], s[24:25], 0, v[134:135]
	s_add_i32 m0, s30, 0x2000
	s_nop 0
	global_load_lds_dwordx4 v[226:227], off
	s_barrier
	s_waitcnt lgkmcnt(0)
	s_setprio 1
	s_waitcnt lgkmcnt(0)
	v_mfma_f32_16x16x32_bf16 v[116:119], v[208:211], v[174:177], 0
	v_mfma_f32_16x16x32_bf16 v[112:115], v[218:221], v[174:177], 0
	v_mfma_f32_16x16x32_bf16 v[100:103], v[208:211], v[182:185], 0
	v_mfma_f32_16x16x32_bf16 v[96:99], v[218:221], v[182:185], 0
	v_mfma_f32_16x16x32_bf16 v[84:87], v[208:211], v[192:195], 0
	v_mfma_f32_16x16x32_bf16 v[80:83], v[218:221], v[192:195], 0
	v_mfma_f32_16x16x32_bf16 v[68:71], v[208:211], v[200:203], 0
	v_mfma_f32_16x16x32_bf16 v[64:67], v[218:221], v[200:203], 0
	v_mfma_f32_16x16x32_bf16 v[116:119], v[214:217], v[178:181], v[116:119]
	v_mfma_f32_16x16x32_bf16 v[112:115], v[222:225], v[178:181], v[112:115]
	v_mfma_f32_16x16x32_bf16 v[100:103], v[214:217], v[186:189], v[100:103]
	v_mfma_f32_16x16x32_bf16 v[96:99], v[222:225], v[186:189], v[96:99]
	v_mfma_f32_16x16x32_bf16 v[84:87], v[214:217], v[196:199], v[84:87]
	v_mfma_f32_16x16x32_bf16 v[80:83], v[222:225], v[196:199], v[80:83]
	v_mfma_f32_16x16x32_bf16 v[68:71], v[214:217], v[204:207], v[68:71]
	v_mfma_f32_16x16x32_bf16 v[64:67], v[222:225], v[204:207], v[64:67]
	s_setprio 0
	s_mov_b32 m0, s43
	v_lshl_add_u64 v[228:229], s[26:27], 0, v[128:129]
	s_barrier
	ds_read_b128 v[174:177], v152 offset:16384
	ds_read_b128 v[178:181], v152 offset:17408
	ds_read_b128 v[182:185], v152 offset:18432
	ds_read_b128 v[186:189], v152 offset:19456
	ds_read_b128 v[192:195], v152 offset:20480
	ds_read_b128 v[196:199], v152 offset:21504
	ds_read_b128 v[200:203], v152 offset:22528
	ds_read_b128 v[204:207], v152 offset:23552
	global_load_lds_dwordx4 v[228:229], off
	v_lshl_add_u64 v[230:231], s[26:27], 0, v[132:133]
	s_mov_b32 m0, s44
	s_nop 0
	global_load_lds_dwordx4 v[230:231], off
	s_barrier
	s_waitcnt lgkmcnt(0)
	s_setprio 1
	s_waitcnt lgkmcnt(0)
	v_mfma_f32_16x16x32_bf16 v[60:63], v[158:161], v[174:177], 0
	v_mfma_f32_16x16x32_bf16 v[56:59], v[166:169], v[174:177], 0
	v_mfma_f32_16x16x32_bf16 v[44:47], v[158:161], v[182:185], 0
	v_mfma_f32_16x16x32_bf16 v[40:43], v[166:169], v[182:185], 0
	v_mfma_f32_16x16x32_bf16 v[28:31], v[158:161], v[192:195], 0
	v_mfma_f32_16x16x32_bf16 v[24:27], v[166:169], v[192:195], 0
	v_mfma_f32_16x16x32_bf16 v[12:15], v[158:161], v[200:203], 0
	v_mfma_f32_16x16x32_bf16 v[8:11], v[166:169], v[200:203], 0
	v_mfma_f32_16x16x32_bf16 v[60:63], v[162:165], v[178:181], v[60:63]
	v_mfma_f32_16x16x32_bf16 v[56:59], v[170:173], v[178:181], v[56:59]
	v_mfma_f32_16x16x32_bf16 v[44:47], v[162:165], v[186:189], v[44:47]
	v_mfma_f32_16x16x32_bf16 v[40:43], v[170:173], v[186:189], v[40:43]
	v_mfma_f32_16x16x32_bf16 v[28:31], v[162:165], v[196:199], v[28:31]
	v_mfma_f32_16x16x32_bf16 v[24:27], v[170:173], v[196:199], v[24:27]
	v_mfma_f32_16x16x32_bf16 v[12:15], v[162:165], v[204:207], v[12:15]
	v_mfma_f32_16x16x32_bf16 v[8:11], v[170:173], v[204:207], v[8:11]
	s_setprio 0
	s_barrier
; #define PG8_STAGE(bufoff, gbase, voff) do { _Pragma("unroll") for (int _i = 0; _i < 2; ++_i) \
;         __builtin_amdgcn_global_load_lds((const unsigned*)((const char*)(gbase) + (voff)[_i]), (LAS unsigned*)(lds + (bufoff) + ldsw + _i * 8192), 16, 0, 0); } while (0)
; #define PG8_LDA(dst, b, h) do { _Pragma("unroll") for (int m = 0; m < 4; ++m) _Pragma("unroll") for (int k = 0; k < 2; ++k) dst[m][k] = *(const LAS bf16x8*)(lds + PG8_SA(b, h) + aoff + m * 2048 + k * 1024); } while (0)
; #define PG8_LDB(dst, b, h) do { _Pragma("unroll") for (int n = 0; n < 2; ++n) _Pragma("unroll") for (int k = 0; k < 2; ++k) dst[n][k] = *(const LAS bf16x8*)(lds + PG8_SB(b, h) + boff + n * 2048 + k * 1024); } while (0)
; #define PG8_MMA(ai, bj, At, Bt) do { __builtin_amdgcn_s_setprio(1); _Pragma("unroll") for (int m = 0; m < 4; ++m) _Pragma("unroll") for (int n = 0; n < 2; ++n) _Pragma("unroll") for (int k = 0; k < 2; ++k) \
;         acc[ai][bj][m][n] = __builtin_amdgcn_mfma_f32_16x16x32_bf16(Bt[n][k], At[m][k], acc[ai][bj][m][n], 0, 0, 0); __builtin_amdgcn_s_setprio(0); } while (0)
; #define PG8_WAIT_V(n) asm volatile("s_waitcnt vmcnt(" #n ")" ::: "memory")
; #define PG8_WAIT_L(n) asm volatile("s_waitcnt lgkmcnt(" #n ")" ::: "memory")
; #define PG8_BAR __builtin_amdgcn_s_barrier()
; #define PG8_SCHED __builtin_amdgcn_sched_barrier(0)
; #define PG8_LDA(dst, b, h) do { _Pragma("unroll") for (int m = 0; m < 4; ++m) _Pragma("unroll") for (int k = 0; k < 2; ++k) dst[m][k] = *(const LAS bf16x8*)(lds + PG8_SA(b, h) + aoff + m * 2048 + k * 1024); } while (0)
; #define PG8_BAR __builtin_amdgcn_s_barrier()
; template <class Epi, bool AFTER = false>
; __device__ __forceinline__ void gemm_phase(LAS unsigned char* lds, const Gemm g, const StaticOrder& S, const Epi& E) {
;     ...
;             PG8_STAGE(PG8_SB(0, 1), b2 + hstep, voffB);
;             PG8_WAIT_V(6); PG8_BAR; PG8_MMA(1, 1, At, B1); PG8_BAR;
;             PG8_LDB(B0, 1, 0); PG8_SCHED; PG8_LDA(At, 1, 0); PG8_STAGE(PG8_SA(0, 1), a2 + hstep, voffA);
;             PG8_WAIT_L(8); PG8_BAR; PG8_WAIT_L(0); PG8_MMA(0, 0, At, B0); PG8_BAR; PG8_SCHED;
;             PG8_LDB(B1, 1, 1); PG8_STAGE(PG8_SB(1, 0), b3, voffB);
;             PG8_BAR; PG8_WAIT_L(0); PG8_MMA(0, 1, At, B1); PG8_BAR;
;             PG8_LDA(At, 1, 1); PG8_STAGE(PG8_SA(1, 0), a3, voffA);
;             PG8_BAR; PG8_WAIT_L(0); PG8_MMA(1, 0, At, B0); PG8_BAR; PG8_SCHED;
	s_add_u32 s30, s24, 0x40000
	s_addc_u32 s31, s25, 0
	s_add_i32 s34, s59, s42
	v_lshl_add_u64 v[158:159], s[30:31], 0, v[130:131]
	s_mov_b32 m0, s34
	s_nop 0
	global_load_lds_dwordx4 v[158:159], off
	v_lshl_add_u64 v[158:159], s[30:31], 0, v[134:135]
	s_add_i32 m0, s34, 0x2000
	s_nop 0
	global_load_lds_dwordx4 v[158:159], off
	s_waitcnt vmcnt(6)
	s_barrier
	s_setprio 1
	v_mfma_f32_16x16x32_bf16 v[52:55], v[208:211], v[174:177], 0
	v_mfma_f32_16x16x32_bf16 v[48:51], v[218:221], v[174:177], 0
	v_mfma_f32_16x16x32_bf16 v[36:39], v[208:211], v[182:185], 0
	v_mfma_f32_16x16x32_bf16 v[32:35], v[218:221], v[182:185], 0
	v_mfma_f32_16x16x32_bf16 v[20:23], v[208:211], v[192:195], 0
	v_mfma_f32_16x16x32_bf16 v[16:19], v[218:221], v[192:195], 0
	v_mfma_f32_16x16x32_bf16 v[4:7], v[208:211], v[200:203], 0
	v_mfma_f32_16x16x32_bf16 v[0:3], v[218:221], v[200:203], 0
	v_mfma_f32_16x16x32_bf16 v[52:55], v[214:217], v[178:181], v[52:55]
	v_mfma_f32_16x16x32_bf16 v[48:51], v[222:225], v[178:181], v[48:51]
	v_mfma_f32_16x16x32_bf16 v[36:39], v[214:217], v[186:189], v[36:39]
	v_mfma_f32_16x16x32_bf16 v[32:35], v[222:225], v[186:189], v[32:35]
	v_mfma_f32_16x16x32_bf16 v[20:23], v[214:217], v[196:199], v[20:23]
	v_mfma_f32_16x16x32_bf16 v[16:19], v[222:225], v[196:199], v[16:19]
	v_mfma_f32_16x16x32_bf16 v[4:7], v[214:217], v[204:207], v[4:7]
	v_mfma_f32_16x16x32_bf16 v[0:3], v[222:225], v[204:207], v[0:3]
	s_setprio 0
	s_add_i32 s30, 0, 0x18000
	v_add_u32_e32 v136, s30, v150
	s_barrier
	ds_read_b128 v[158:161], v136
	ds_read_b128 v[162:165], v136 offset:1024
	ds_read_b128 v[166:169], v136 offset:2048
	ds_read_b128 v[170:173], v136 offset:3072
	s_add_u32 s26, s26, 0x40000
	s_addc_u32 s27, s27, 0
	s_mov_b32 m0, s45
	v_lshl_add_u64 v[208:209], s[26:27], 0, v[128:129]
	ds_read_b128 v[174:177], v152 offset:32768
	ds_read_b128 v[178:181], v152 offset:33792
	ds_read_b128 v[182:185], v152 offset:34816
	ds_read_b128 v[186:189], v152 offset:35840
	ds_read_b128 v[192:195], v152 offset:36864
	ds_read_b128 v[196:199], v152 offset:37888
	ds_read_b128 v[200:203], v152 offset:38912
	ds_read_b128 v[204:207], v152 offset:39936
	global_load_lds_dwordx4 v[208:209], off
	v_lshl_add_u64 v[208:209], s[26:27], 0, v[132:133]
	s_mov_b32 m0, s46
	s_nop 0
	global_load_lds_dwordx4 v[208:209], off
	s_waitcnt lgkmcnt(8)
	s_barrier
	s_waitcnt lgkmcnt(0)
	s_setprio 1
	s_waitcnt lgkmcnt(0)
	v_mfma_f32_16x16x32_bf16 v[124:127], v[158:161], v[174:177], v[124:127]
	v_mfma_f32_16x16x32_bf16 v[120:123], v[166:169], v[174:177], v[120:123]
	v_mfma_f32_16x16x32_bf16 v[108:111], v[158:161], v[182:185], v[108:111]
	v_mfma_f32_16x16x32_bf16 v[104:107], v[166:169], v[182:185], v[104:107]
	v_mfma_f32_16x16x32_bf16 v[92:95], v[158:161], v[192:195], v[92:95]
	v_mfma_f32_16x16x32_bf16 v[88:91], v[166:169], v[192:195], v[88:91]
	v_mfma_f32_16x16x32_bf16 v[76:79], v[158:161], v[200:203], v[76:79]
	v_mfma_f32_16x16x32_bf16 v[72:75], v[166:169], v[200:203], v[72:75]
	v_mfma_f32_16x16x32_bf16 v[124:127], v[162:165], v[178:181], v[124:127]
	v_mfma_f32_16x16x32_bf16 v[120:123], v[170:173], v[178:181], v[120:123]
	v_mfma_f32_16x16x32_bf16 v[108:111], v[162:165], v[186:189], v[108:111]
	v_mfma_f32_16x16x32_bf16 v[104:107], v[170:173], v[186:189], v[104:107]
	v_mfma_f32_16x16x32_bf16 v[92:95], v[162:165], v[196:199], v[92:95]
	v_mfma_f32_16x16x32_bf16 v[88:91], v[170:173], v[196:199], v[88:91]
	v_mfma_f32_16x16x32_bf16 v[76:79], v[162:165], v[204:207], v[76:79]
	v_mfma_f32_16x16x32_bf16 v[72:75], v[170:173], v[204:207], v[72:75]
	s_setprio 0
	s_barrier
	s_add_i32 s26, 0, 0x1c000
	s_add_i32 s27, s30, s42
	v_add_u32_e32 v136, s26, v150
	v_lshl_add_u64 v[148:149], v[148:149], 0, s[10:11]
	s_mov_b32 m0, s27
	ds_read_b128 v[208:211], v136
	ds_read_b128 v[214:217], v136 offset:1024
	ds_read_b128 v[218:221], v136 offset:2048
	ds_read_b128 v[222:225], v136 offset:3072
	global_load_lds_dwordx4 v[148:149], off
	v_lshl_add_u64 v[148:149], v[226:227], 0, s[10:11]
	s_add_i32 m0, s27, 0x2000
	s_nop 0
	global_load_lds_dwordx4 v[148:149], off
	s_barrier
; #define PG8_STAGE(bufoff, gbase, voff) do { _Pragma("unroll") for (int _i = 0; _i < 2; ++_i) \
;         __builtin_amdgcn_global_load_lds((const unsigned*)((const char*)(gbase) + (voff)[_i]), (LAS unsigned*)(lds + (bufoff) + ldsw + _i * 8192), 16, 0, 0); } while (0)
; #define PG8_MMA(ai, bj, At, Bt) do { __builtin_amdgcn_s_setprio(1); _Pragma("unroll") for (int m = 0; m < 4; ++m) _Pragma("unroll") for (int n = 0; n < 2; ++n) _Pragma("unroll") for (int k = 0; k < 2; ++k) \
;         acc[ai][bj][m][n] = __builtin_amdgcn_mfma_f32_16x16x32_bf16(Bt[n][k], At[m][k], acc[ai][bj][m][n], 0, 0, 0); __builtin_amdgcn_s_setprio(0); } while (0)
; #define PG8_WAIT_V(n) asm volatile("s_waitcnt vmcnt(" #n ")" ::: "memory")
; #define PG8_WAIT_L(n) asm volatile("s_waitcnt lgkmcnt(" #n ")" ::: "memory")
; #define PG8_BAR __builtin_amdgcn_s_barrier()
; #define PG8_SCHED __builtin_amdgcn_sched_barrier(0)
; #define PG8_MMA(ai, bj, At, Bt) do { __builtin_amdgcn_s_setprio(1); _Pragma("unroll") for (int m = 0; m < 4; ++m) _Pragma("unroll") for (int n = 0; n < 2; ++n) _Pragma("unroll") for (int k = 0; k < 2; ++k) \
;         acc[ai][bj][m][n] = __builtin_amdgcn_mfma_f32_16x16x32_bf16(Bt[n][k], At[m][k], acc[ai][bj][m][n], 0, 0, 0); __builtin_amdgcn_s_setprio(0); } while (0)
; #define PG8_WAIT_V(n) asm volatile("s_waitcnt vmcnt(" #n ")" ::: "memory")
; #define PG8_WAIT_L(n) asm volatile("s_waitcnt lgkmcnt(" #n ")" ::: "memory")
; #define PG8_BAR __builtin_amdgcn_s_barrier()
; #define PG8_SCHED __builtin_amdgcn_sched_barrier(0)
; template <class Epi, bool AFTER = false>
; __device__ __forceinline__ void gemm_phase(LAS unsigned char* lds, const Gemm g, const StaticOrder& S, const Epi& E) {
;     ...
;             PG8_BAR; PG8_WAIT_L(0); PG8_MMA(1, 0, At, B0); PG8_BAR; PG8_SCHED;
;             PG8_STAGE(PG8_SB(1, 1), b3 + hstep, voffB);
;             PG8_WAIT_V(6); PG8_BAR; PG8_MMA(1, 1, At, B1); PG8_BAR;
	s_waitcnt lgkmcnt(0)
	s_setprio 1
	s_waitcnt lgkmcnt(0)
	v_mfma_f32_16x16x32_bf16 v[116:119], v[208:211], v[174:177], v[116:119]
	v_mfma_f32_16x16x32_bf16 v[112:115], v[218:221], v[174:177], v[112:115]
	v_mfma_f32_16x16x32_bf16 v[100:103], v[208:211], v[182:185], v[100:103]
	v_mfma_f32_16x16x32_bf16 v[96:99], v[218:221], v[182:185], v[96:99]
	v_mfma_f32_16x16x32_bf16 v[84:87], v[208:211], v[192:195], v[84:87]
	v_mfma_f32_16x16x32_bf16 v[80:83], v[218:221], v[192:195], v[80:83]
	v_mfma_f32_16x16x32_bf16 v[68:71], v[208:211], v[200:203], v[68:71]
	v_mfma_f32_16x16x32_bf16 v[64:67], v[218:221], v[200:203], v[64:67]
	v_mfma_f32_16x16x32_bf16 v[116:119], v[214:217], v[178:181], v[116:119]
	v_mfma_f32_16x16x32_bf16 v[112:115], v[222:225], v[178:181], v[112:115]
	v_mfma_f32_16x16x32_bf16 v[100:103], v[214:217], v[186:189], v[100:103]
	v_mfma_f32_16x16x32_bf16 v[96:99], v[222:225], v[186:189], v[96:99]
	v_mfma_f32_16x16x32_bf16 v[84:87], v[214:217], v[196:199], v[84:87]
	v_mfma_f32_16x16x32_bf16 v[80:83], v[222:225], v[196:199], v[80:83]
	v_mfma_f32_16x16x32_bf16 v[68:71], v[214:217], v[204:207], v[68:71]
	v_mfma_f32_16x16x32_bf16 v[64:67], v[222:225], v[204:207], v[64:67]
	s_setprio 0
	s_mov_b32 m0, s54
	v_lshl_add_u64 v[148:149], v[228:229], 0, s[10:11]
	s_barrier
	ds_read_b128 v[174:177], v152 offset:49152
	ds_read_b128 v[178:181], v152 offset:50176
	ds_read_b128 v[182:185], v152 offset:51200
	ds_read_b128 v[186:189], v152 offset:52224
	ds_read_b128 v[192:195], v152 offset:53248
	ds_read_b128 v[196:199], v152 offset:54272
	ds_read_b128 v[200:203], v152 offset:55296
	ds_read_b128 v[204:207], v152 offset:56320
	global_load_lds_dwordx4 v[148:149], off
	v_lshl_add_u64 v[148:149], v[230:231], 0, s[10:11]
	s_mov_b32 m0, s55
	s_nop 0
	global_load_lds_dwordx4 v[148:149], off
	s_barrier
	s_waitcnt lgkmcnt(0)
	s_setprio 1
	s_waitcnt lgkmcnt(0)
	v_mfma_f32_16x16x32_bf16 v[60:63], v[158:161], v[174:177], v[60:63]
	v_mfma_f32_16x16x32_bf16 v[56:59], v[166:169], v[174:177], v[56:59]
	v_mfma_f32_16x16x32_bf16 v[44:47], v[158:161], v[182:185], v[44:47]
	v_mfma_f32_16x16x32_bf16 v[40:43], v[166:169], v[182:185], v[40:43]
	v_mfma_f32_16x16x32_bf16 v[28:31], v[158:161], v[192:195], v[28:31]
	v_mfma_f32_16x16x32_bf16 v[24:27], v[166:169], v[192:195], v[24:27]
	v_mfma_f32_16x16x32_bf16 v[12:15], v[158:161], v[200:203], v[12:15]
	v_mfma_f32_16x16x32_bf16 v[8:11], v[166:169], v[200:203], v[8:11]
	v_mfma_f32_16x16x32_bf16 v[60:63], v[162:165], v[178:181], v[60:63]
	v_mfma_f32_16x16x32_bf16 v[56:59], v[170:173], v[178:181], v[56:59]
	v_mfma_f32_16x16x32_bf16 v[44:47], v[162:165], v[186:189], v[44:47]
	v_mfma_f32_16x16x32_bf16 v[40:43], v[170:173], v[186:189], v[40:43]
	v_mfma_f32_16x16x32_bf16 v[28:31], v[162:165], v[196:199], v[28:31]
	v_mfma_f32_16x16x32_bf16 v[24:27], v[170:173], v[196:199], v[24:27]
	v_mfma_f32_16x16x32_bf16 v[12:15], v[162:165], v[204:207], v[12:15]
	v_mfma_f32_16x16x32_bf16 v[8:11], v[170:173], v[204:207], v[8:11]
	s_setprio 0
	s_barrier
	s_add_u32 s24, s24, 0x40080
	s_addc_u32 s25, s25, 0
	s_add_i32 s26, s26, s42
	v_lshl_add_u64 v[148:149], s[24:25], 0, v[130:131]
	s_mov_b32 m0, s26
	s_nop 0
	global_load_lds_dwordx4 v[148:149], off
	v_lshl_add_u64 v[148:149], s[24:25], 0, v[134:135]
	s_add_i32 m0, s26, 0x2000
	s_nop 0
	global_load_lds_dwordx4 v[148:149], off
	s_waitcnt vmcnt(6)
	s_barrier
	s_setprio 1
	v_mfma_f32_16x16x32_bf16 v[52:55], v[208:211], v[174:177], v[52:55]
	v_mfma_f32_16x16x32_bf16 v[48:51], v[218:221], v[174:177], v[48:51]
	v_mfma_f32_16x16x32_bf16 v[36:39], v[208:211], v[182:185], v[36:39]
	v_mfma_f32_16x16x32_bf16 v[32:35], v[218:221], v[182:185], v[32:35]
	v_mfma_f32_16x16x32_bf16 v[20:23], v[208:211], v[192:195], v[20:23]
	v_mfma_f32_16x16x32_bf16 v[16:19], v[218:221], v[192:195], v[16:19]
	v_mfma_f32_16x16x32_bf16 v[4:7], v[208:211], v[200:203], v[4:7]
	v_mfma_f32_16x16x32_bf16 v[0:3], v[218:221], v[200:203], v[0:3]
	v_mfma_f32_16x16x32_bf16 v[52:55], v[214:217], v[178:181], v[52:55]
	v_mfma_f32_16x16x32_bf16 v[48:51], v[222:225], v[178:181], v[48:51]
	v_mfma_f32_16x16x32_bf16 v[36:39], v[214:217], v[186:189], v[36:39]
	v_mfma_f32_16x16x32_bf16 v[32:35], v[222:225], v[186:189], v[32:35]
	v_mfma_f32_16x16x32_bf16 v[20:23], v[214:217], v[196:199], v[20:23]
	v_mfma_f32_16x16x32_bf16 v[16:19], v[222:225], v[196:199], v[16:19]
	v_mfma_f32_16x16x32_bf16 v[4:7], v[214:217], v[204:207], v[4:7]
	v_mfma_f32_16x16x32_bf16 v[0:3], v[222:225], v[204:207], v[0:3]
	s_setprio 0
	s_add_i32 s29, s29, 2
	s_add_u32 s22, s22, 0x100
	s_addc_u32 s23, s23, 0
	s_add_u32 s17, s17, 0x100
	s_addc_u32 s28, s28, 0
	s_cmp_gt_u32 s29, 13
	s_nop 0
	s_nop 0
	s_nop 0
	s_nop 0
	s_nop 0
	s_nop 0
	s_nop 0
	s_nop 0
	s_nop 0
	s_nop 0
	s_barrier

; #define PG8_STAGE(bufoff, gbase, voff) do { _Pragma("unroll") for (int _i = 0; _i < 2; ++_i) \
;         __builtin_amdgcn_global_load_lds((const unsigned*)((const char*)(gbase) + (voff)[_i]), (LAS unsigned*)(lds + (bufoff) + ldsw + _i * 8192), 16, 0, 0); } while (0)
; #define PG8_LDA(dst, b, h) do { _Pragma("unroll") for (int m = 0; m < 4; ++m) _Pragma("unroll") for (int k = 0; k < 2; ++k) dst[m][k] = *(const LAS bf16x8*)(lds + PG8_SA(b, h) + aoff + m * 2048 + k * 1024); } while (0)
; #define PG8_LDB(dst, b, h) do { _Pragma("unroll") for (int n = 0; n < 2; ++n) _Pragma("unroll") for (int k = 0; k < 2; ++k) dst[n][k] = *(const LAS bf16x8*)(lds + PG8_SB(b, h) + boff + n * 2048 + k * 1024); } while (0)
; #define PG8_MMA(ai, bj, At, Bt) do { __builtin_amdgcn_s_setprio(1); _Pragma("unroll") for (int m = 0; m < 4; ++m) _Pragma("unroll") for (int n = 0; n < 2; ++n) _Pragma("unroll") for (int k = 0; k < 2; ++k) \
;         acc[ai][bj][m][n] = __builtin_amdgcn_mfma_f32_16x16x32_bf16(Bt[n][k], At[m][k], acc[ai][bj][m][n], 0, 0, 0); __builtin_amdgcn_s_setprio(0); } while (0)
; #define PG8_WAIT_L(n) asm volatile("s_waitcnt lgkmcnt(" #n ")" ::: "memory")
; template <class Epi, bool AFTER = false>
; __device__ __forceinline__ void gemm_phase(LAS unsigned char* lds, const Gemm g, const StaticOrder& S, const Epi& E) {
;     ...
;         const bool has_next = S.next(ui + 1, nxt);
;         const char* nA = has_next ? (const char*)g.A + (size_t)nxt.pm * tstep : cA; const char* nB = has_next ? (const char*)g.Bt + (size_t)nxt.pn * tstep : cB;
;         for (int t = 0; t < nt; t += 2) {
;             const bool last = (t == nt - 2);
;             const char* a1 = cA + (size_t)(t + 1) * kstep;
;             const char* a2 = last ? nA : cA + (size_t)(t + 2) * kstep; const char* b2 = last ? nB : cB + (size_t)(t + 2) * kstep;
;             const char* a3 = a2 + kstep; const char* b3 = b2 + kstep;
;             PG8_LDB(B0, 0, 0); PG8_SCHED; PG8_LDA(At, 0, 0); PG8_STAGE(PG8_SA(1, 1), a1 + hstep, voffA);
;             PG8_WAIT_L(8); PG8_BAR; PG8_WAIT_L(0); PG8_MMA(0, 0, At, B0); PG8_BAR; PG8_SCHED;
;             PG8_LDB(B1, 0, 1); PG8_STAGE(PG8_SB(0, 0), b2, voffB);
;             PG8_BAR; PG8_WAIT_L(0); PG8_MMA(0, 1, At, B1); PG8_BAR;
;             PG8_LDA(At, 0, 1); PG8_STAGE(PG8_SA(0, 0), a2, voffA);
;             PG8_BAR; PG8_WAIT_L(0); PG8_MMA(1, 0, At, B0); PG8_BAR; PG8_SCHED;
.LBB0_846:
	s_ashr_i32 s23, s22, 31
	v_cmp_lt_i64_e32 vcc, s[24:25], v[140:141]
	s_lshl_b64 s[24:25], s[22:23], 19
	s_add_u32 s24, s33, s24
	s_addc_u32 s25, s36, s25
	s_and_b64 s[26:27], vcc, exec
	s_cselect_b32 s23, s25, s29
	s_cselect_b32 s56, s24, s28
	s_ashr_i32 s21, s20, 31
	s_lshl_b64 s[26:27], s[20:21], 19
	s_add_u32 s26, s37, s26
	s_addc_u32 s27, s38, s27
	s_and_b64 s[34:35], vcc, exec
	s_cselect_b32 s21, s27, s31
	s_cselect_b32 s57, s26, s30
	s_add_u32 s28, s28, 0x40080
	s_addc_u32 s29, s29, 0
	s_add_u32 s58, s30, 0x100
	s_addc_u32 s59, s31, 0
	s_mov_b32 s60, -2
	ds_read_b128 v[150:153], v147
	ds_read_b128 v[154:157], v147 offset:1024
	ds_read_b128 v[158:161], v147 offset:2048
	ds_read_b128 v[162:165], v147 offset:3072
	s_add_u32 s30, s28, 0xfffc0080
	s_addc_u32 s31, s29, -1
	s_cmp_eq_u32 s60, 12
	s_cselect_b32 s35, s23, s31
	s_cselect_b32 s34, s56, s30
	s_cselect_b32 s31, s21, s59
	s_cselect_b32 s30, s57, s58
	v_lshl_add_u64 v[198:199], s[28:29], 0, v[136:137]
	s_add_i32 m0, s9, 0xc000
	ds_read_b128 v[166:169], v148
	ds_read_b128 v[170:173], v148 offset:1024
	ds_read_b128 v[174:177], v148 offset:2048
	ds_read_b128 v[178:181], v148 offset:3072
	ds_read_b128 v[182:185], v148 offset:4096
	ds_read_b128 v[186:189], v148 offset:5120
	ds_read_b128 v[190:193], v148 offset:6144
	ds_read_b128 v[194:197], v148 offset:7168
	global_load_lds_dwordx4 v[198:199], off
	v_lshl_add_u64 v[198:199], s[28:29], 0, v[138:139]
	s_add_i32 m0, s9, 0xe000
	s_nop 0
	global_load_lds_dwordx4 v[198:199], off
	s_waitcnt lgkmcnt(8)
	s_barrier
	s_waitcnt lgkmcnt(0)
	s_setprio 1
	s_waitcnt lgkmcnt(0)
	v_mfma_f32_16x16x32_bf16 v[124:127], v[150:153], v[166:169], 0
	v_mfma_f32_16x16x32_bf16 v[120:123], v[158:161], v[166:169], 0
	v_mfma_f32_16x16x32_bf16 v[116:119], v[150:153], v[174:177], 0
	v_mfma_f32_16x16x32_bf16 v[112:115], v[158:161], v[174:177], 0
	v_mfma_f32_16x16x32_bf16 v[100:103], v[150:153], v[182:185], 0
	v_mfma_f32_16x16x32_bf16 v[96:99], v[158:161], v[182:185], 0
	v_mfma_f32_16x16x32_bf16 v[84:87], v[150:153], v[190:193], 0
	v_mfma_f32_16x16x32_bf16 v[80:83], v[158:161], v[190:193], 0
	v_mfma_f32_16x16x32_bf16 v[124:127], v[154:157], v[170:173], v[124:127]
	v_mfma_f32_16x16x32_bf16 v[120:123], v[162:165], v[170:173], v[120:123]
	v_mfma_f32_16x16x32_bf16 v[116:119], v[154:157], v[178:181], v[116:119]
	v_mfma_f32_16x16x32_bf16 v[112:115], v[162:165], v[178:181], v[112:115]
	v_mfma_f32_16x16x32_bf16 v[100:103], v[154:157], v[186:189], v[100:103]
	v_mfma_f32_16x16x32_bf16 v[96:99], v[162:165], v[186:189], v[96:99]
	v_mfma_f32_16x16x32_bf16 v[84:87], v[154:157], v[194:197], v[84:87]
	v_mfma_f32_16x16x32_bf16 v[80:83], v[162:165], v[194:197], v[80:83]
	s_setprio 0
	s_barrier
	s_add_i32 s61, s50, s41
	v_lshl_add_u64 v[210:211], s[30:31], 0, v[130:131]
	s_mov_b32 m0, s61
	ds_read_b128 v[198:201], v149
	ds_read_b128 v[202:205], v149 offset:1024
	ds_read_b128 v[206:209], v149 offset:2048
	ds_read_b128 v[214:217], v149 offset:3072
	global_load_lds_dwordx4 v[210:211], off
	v_lshl_add_u64 v[218:219], s[30:31], 0, v[134:135]
	s_add_i32 m0, s61, 0x2000
	s_nop 0
	global_load_lds_dwordx4 v[218:219], off
	s_barrier
	s_waitcnt lgkmcnt(0)
	s_setprio 1
	s_waitcnt lgkmcnt(0)
	v_mfma_f32_16x16x32_bf16 v[108:111], v[198:201], v[166:169], 0
	v_mfma_f32_16x16x32_bf16 v[104:107], v[206:209], v[166:169], 0
	v_mfma_f32_16x16x32_bf16 v[92:95], v[198:201], v[174:177], 0
	v_mfma_f32_16x16x32_bf16 v[88:91], v[206:209], v[174:177], 0
	v_mfma_f32_16x16x32_bf16 v[76:79], v[198:201], v[182:185], 0
	v_mfma_f32_16x16x32_bf16 v[72:75], v[206:209], v[182:185], 0
	v_mfma_f32_16x16x32_bf16 v[68:71], v[198:201], v[190:193], 0
	v_mfma_f32_16x16x32_bf16 v[64:67], v[206:209], v[190:193], 0
	v_mfma_f32_16x16x32_bf16 v[108:111], v[202:205], v[170:173], v[108:111]
	v_mfma_f32_16x16x32_bf16 v[104:107], v[214:217], v[170:173], v[104:107]
	v_mfma_f32_16x16x32_bf16 v[92:95], v[202:205], v[178:181], v[92:95]
	v_mfma_f32_16x16x32_bf16 v[88:91], v[214:217], v[178:181], v[88:91]
	v_mfma_f32_16x16x32_bf16 v[76:79], v[202:205], v[186:189], v[76:79]
	v_mfma_f32_16x16x32_bf16 v[72:75], v[214:217], v[186:189], v[72:75]
	v_mfma_f32_16x16x32_bf16 v[68:71], v[202:205], v[194:197], v[68:71]
	v_mfma_f32_16x16x32_bf16 v[64:67], v[214:217], v[194:197], v[64:67]
	s_setprio 0
	s_mov_b32 m0, s9
	v_lshl_add_u64 v[220:221], s[34:35], 0, v[128:129]
	s_barrier
	ds_read_b128 v[166:169], v148 offset:16384
	ds_read_b128 v[170:173], v148 offset:17408
	ds_read_b128 v[174:177], v148 offset:18432
	ds_read_b128 v[178:181], v148 offset:19456
	ds_read_b128 v[182:185], v148 offset:20480
	ds_read_b128 v[186:189], v148 offset:21504
	ds_read_b128 v[190:193], v148 offset:22528
	ds_read_b128 v[194:197], v148 offset:23552
	global_load_lds_dwordx4 v[220:221], off
	v_lshl_add_u64 v[222:223], s[34:35], 0, v[132:133]
	s_mov_b32 m0, s42
	s_nop 0
	global_load_lds_dwordx4 v[222:223], off
	s_barrier
	s_waitcnt lgkmcnt(0)
	s_setprio 1
	s_waitcnt lgkmcnt(0)
	v_mfma_f32_16x16x32_bf16 v[60:63], v[150:153], v[166:169], 0
	v_mfma_f32_16x16x32_bf16 v[56:59], v[158:161], v[166:169], 0
	v_mfma_f32_16x16x32_bf16 v[52:55], v[150:153], v[174:177], 0
	v_mfma_f32_16x16x32_bf16 v[48:51], v[158:161], v[174:177], 0
	v_mfma_f32_16x16x32_bf16 v[40:43], v[150:153], v[182:185], 0
	v_mfma_f32_16x16x32_bf16 v[32:35], v[158:161], v[182:185], 0
	v_mfma_f32_16x16x32_bf16 v[24:27], v[150:153], v[190:193], 0
	v_mfma_f32_16x16x32_bf16 v[16:19], v[158:161], v[190:193], 0
	v_mfma_f32_16x16x32_bf16 v[60:63], v[154:157], v[170:173], v[60:63]
	v_mfma_f32_16x16x32_bf16 v[56:59], v[162:165], v[170:173], v[56:59]
	v_mfma_f32_16x16x32_bf16 v[52:55], v[154:157], v[178:181], v[52:55]
	v_mfma_f32_16x16x32_bf16 v[48:51], v[162:165], v[178:181], v[48:51]
	v_mfma_f32_16x16x32_bf16 v[40:43], v[154:157], v[186:189], v[40:43]
	v_mfma_f32_16x16x32_bf16 v[32:35], v[162:165], v[186:189], v[32:35]
	v_mfma_f32_16x16x32_bf16 v[24:27], v[154:157], v[194:197], v[24:27]
	v_mfma_f32_16x16x32_bf16 v[16:19], v[162:165], v[194:197], v[16:19]
	s_setprio 0
	s_barrier
; #define PG8_STAGE(bufoff, gbase, voff) do { _Pragma("unroll") for (int _i = 0; _i < 2; ++_i) \
;         __builtin_amdgcn_global_load_lds((const unsigned*)((const char*)(gbase) + (voff)[_i]), (LAS unsigned*)(lds + (bufoff) + ldsw + _i * 8192), 16, 0, 0); } while (0)
; #define PG8_LDA(dst, b, h) do { _Pragma("unroll") for (int m = 0; m < 4; ++m) _Pragma("unroll") for (int k = 0; k < 2; ++k) dst[m][k] = *(const LAS bf16x8*)(lds + PG8_SA(b, h) + aoff + m * 2048 + k * 1024); } while (0)
; #define PG8_LDB(dst, b, h) do { _Pragma("unroll") for (int n = 0; n < 2; ++n) _Pragma("unroll") for (int k = 0; k < 2; ++k) dst[n][k] = *(const LAS bf16x8*)(lds + PG8_SB(b, h) + boff + n * 2048 + k * 1024); } while (0)
; #define PG8_MMA(ai, bj, At, Bt) do { __builtin_amdgcn_s_setprio(1); _Pragma("unroll") for (int m = 0; m < 4; ++m) _Pragma("unroll") for (int n = 0; n < 2; ++n) _Pragma("unroll") for (int k = 0; k < 2; ++k) \
;         acc[ai][bj][m][n] = __builtin_amdgcn_mfma_f32_16x16x32_bf16(Bt[n][k], At[m][k], acc[ai][bj][m][n], 0, 0, 0); __builtin_amdgcn_s_setprio(0); } while (0)
; #define PG8_WAIT_V(n) asm volatile("s_waitcnt vmcnt(" #n ")" ::: "memory")
; #define PG8_WAIT_L(n) asm volatile("s_waitcnt lgkmcnt(" #n ")" ::: "memory")
; #define PG8_BAR __builtin_amdgcn_s_barrier()
; #define PG8_SCHED __builtin_amdgcn_sched_barrier(0)
; #define PG8_LDA(dst, b, h) do { _Pragma("unroll") for (int m = 0; m < 4; ++m) _Pragma("unroll") for (int k = 0; k < 2; ++k) dst[m][k] = *(const LAS bf16x8*)(lds + PG8_SA(b, h) + aoff + m * 2048 + k * 1024); } while (0)
; #define PG8_BAR __builtin_amdgcn_s_barrier()
; template <class Epi, bool AFTER = false>
; __device__ __forceinline__ void gemm_phase(LAS unsigned char* lds, const Gemm g, const StaticOrder& S, const Epi& E) {
;     ...
;             PG8_STAGE(PG8_SB(0, 1), b2 + hstep, voffB);
;             PG8_WAIT_V(6); PG8_BAR; PG8_MMA(1, 1, At, B1); PG8_BAR;
;             PG8_LDB(B0, 1, 0); PG8_SCHED; PG8_LDA(At, 1, 0); PG8_STAGE(PG8_SA(0, 1), a2 + hstep, voffA);
;             PG8_WAIT_L(8); PG8_BAR; PG8_WAIT_L(0); PG8_MMA(0, 0, At, B0); PG8_BAR; PG8_SCHED;
;             PG8_LDB(B1, 1, 1); PG8_STAGE(PG8_SB(1, 0), b3, voffB);
;             PG8_BAR; PG8_WAIT_L(0); PG8_MMA(0, 1, At, B1); PG8_BAR;
;             PG8_LDA(At, 1, 1); PG8_STAGE(PG8_SA(1, 0), a3, voffA);
;             PG8_BAR; PG8_WAIT_L(0); PG8_MMA(1, 0, At, B0); PG8_BAR; PG8_SCHED;
	s_add_u32 s62, s30, 0x40000
	s_addc_u32 s63, s31, 0
	s_add_i32 s61, s51, s41
	v_lshl_add_u64 v[150:151], s[62:63], 0, v[130:131]
	s_mov_b32 m0, s61
	s_nop 0
	global_load_lds_dwordx4 v[150:151], off
	v_lshl_add_u64 v[150:151], s[62:63], 0, v[134:135]
	s_add_i32 m0, s61, 0x2000
	s_nop 0
	global_load_lds_dwordx4 v[150:151], off
	s_waitcnt vmcnt(6)
	global_load_dword v242, v240, s[98:99]
	v_add_u32_e32 v240, 0x10000, v240
	s_barrier
	s_setprio 1
	v_mfma_f32_16x16x32_bf16 v[44:47], v[198:201], v[166:169], 0
	v_mfma_f32_16x16x32_bf16 v[36:39], v[206:209], v[166:169], 0
	v_mfma_f32_16x16x32_bf16 v[28:31], v[198:201], v[174:177], 0
	v_mfma_f32_16x16x32_bf16 v[20:23], v[206:209], v[174:177], 0
	v_mfma_f32_16x16x32_bf16 v[12:15], v[198:201], v[182:185], 0
	v_mfma_f32_16x16x32_bf16 v[8:11], v[206:209], v[182:185], 0
	v_mfma_f32_16x16x32_bf16 v[4:7], v[198:201], v[190:193], 0
	v_mfma_f32_16x16x32_bf16 v[0:3], v[206:209], v[190:193], 0
	v_mfma_f32_16x16x32_bf16 v[44:47], v[202:205], v[170:173], v[44:47]
	v_mfma_f32_16x16x32_bf16 v[36:39], v[214:217], v[170:173], v[36:39]
	v_mfma_f32_16x16x32_bf16 v[28:31], v[202:205], v[178:181], v[28:31]
	v_mfma_f32_16x16x32_bf16 v[20:23], v[214:217], v[178:181], v[20:23]
	v_mfma_f32_16x16x32_bf16 v[12:15], v[202:205], v[186:189], v[12:15]
	v_mfma_f32_16x16x32_bf16 v[8:11], v[214:217], v[186:189], v[8:11]
	v_mfma_f32_16x16x32_bf16 v[4:7], v[202:205], v[194:197], v[4:7]
	v_mfma_f32_16x16x32_bf16 v[0:3], v[214:217], v[194:197], v[0:3]
	s_setprio 0
	s_add_i32 s61, 0, 0x18000
	v_add_u32_e32 v162, s61, v145
	s_barrier
	ds_read_b128 v[150:153], v162
	ds_read_b128 v[154:157], v162 offset:1024
	ds_read_b128 v[158:161], v162 offset:2048
	ds_read_b128 v[162:165], v162 offset:3072
	s_add_u32 s34, s34, 0x40000
	s_addc_u32 s35, s35, 0
	s_mov_b32 m0, s43
	v_lshl_add_u64 v[198:199], s[34:35], 0, v[128:129]
	ds_read_b128 v[166:169], v148 offset:32768
	ds_read_b128 v[170:173], v148 offset:33792
	ds_read_b128 v[174:177], v148 offset:34816
	ds_read_b128 v[178:181], v148 offset:35840
	ds_read_b128 v[182:185], v148 offset:36864
	ds_read_b128 v[186:189], v148 offset:37888
	ds_read_b128 v[190:193], v148 offset:38912
	ds_read_b128 v[194:197], v148 offset:39936
	global_load_lds_dwordx4 v[198:199], off
	v_lshl_add_u64 v[198:199], s[34:35], 0, v[132:133]
	s_mov_b32 m0, s44
	s_nop 0
	global_load_lds_dwordx4 v[198:199], off
	s_waitcnt lgkmcnt(8)
	s_barrier
	s_waitcnt lgkmcnt(0)
	s_setprio 1
	s_waitcnt lgkmcnt(0)
	v_mfma_f32_16x16x32_bf16 v[124:127], v[150:153], v[166:169], v[124:127]
	v_mfma_f32_16x16x32_bf16 v[120:123], v[158:161], v[166:169], v[120:123]
	v_mfma_f32_16x16x32_bf16 v[116:119], v[150:153], v[174:177], v[116:119]
	v_mfma_f32_16x16x32_bf16 v[112:115], v[158:161], v[174:177], v[112:115]
	v_mfma_f32_16x16x32_bf16 v[100:103], v[150:153], v[182:185], v[100:103]
	v_mfma_f32_16x16x32_bf16 v[96:99], v[158:161], v[182:185], v[96:99]
	v_mfma_f32_16x16x32_bf16 v[84:87], v[150:153], v[190:193], v[84:87]
	v_mfma_f32_16x16x32_bf16 v[80:83], v[158:161], v[190:193], v[80:83]
	v_mfma_f32_16x16x32_bf16 v[124:127], v[154:157], v[170:173], v[124:127]
	v_mfma_f32_16x16x32_bf16 v[120:123], v[162:165], v[170:173], v[120:123]
	v_mfma_f32_16x16x32_bf16 v[116:119], v[154:157], v[178:181], v[116:119]
	v_mfma_f32_16x16x32_bf16 v[112:115], v[162:165], v[178:181], v[112:115]
	v_mfma_f32_16x16x32_bf16 v[100:103], v[154:157], v[186:189], v[100:103]
	v_mfma_f32_16x16x32_bf16 v[96:99], v[162:165], v[186:189], v[96:99]
	v_mfma_f32_16x16x32_bf16 v[84:87], v[154:157], v[194:197], v[84:87]
	v_mfma_f32_16x16x32_bf16 v[80:83], v[162:165], v[194:197], v[80:83]
	s_setprio 0
	s_barrier
	s_add_i32 s34, 0, 0x1c000
	s_add_i32 s35, s61, s41
	v_add_u32_e32 v213, s34, v145
	v_lshl_add_u64 v[210:211], v[210:211], 0, s[10:11]
	s_mov_b32 m0, s35
	ds_read_b128 v[198:201], v213
	ds_read_b128 v[202:205], v213 offset:1024
	ds_read_b128 v[206:209], v213 offset:2048
	ds_read_b128 v[214:217], v213 offset:3072
	global_load_lds_dwordx4 v[210:211], off
	v_lshl_add_u64 v[210:211], v[218:219], 0, s[10:11]
	s_add_i32 m0, s35, 0x2000
	s_nop 0
	global_load_lds_dwordx4 v[210:211], off
	s_barrier
; #define PG8_STAGE(bufoff, gbase, voff) do { _Pragma("unroll") for (int _i = 0; _i < 2; ++_i) \
;         __builtin_amdgcn_global_load_lds((const unsigned*)((const char*)(gbase) + (voff)[_i]), (LAS unsigned*)(lds + (bufoff) + ldsw + _i * 8192), 16, 0, 0); } while (0)
; #define PG8_MMA(ai, bj, At, Bt) do { __builtin_amdgcn_s_setprio(1); _Pragma("unroll") for (int m = 0; m < 4; ++m) _Pragma("unroll") for (int n = 0; n < 2; ++n) _Pragma("unroll") for (int k = 0; k < 2; ++k) \
;         acc[ai][bj][m][n] = __builtin_amdgcn_mfma_f32_16x16x32_bf16(Bt[n][k], At[m][k], acc[ai][bj][m][n], 0, 0, 0); __builtin_amdgcn_s_setprio(0); } while (0)
; #define PG8_WAIT_V(n) asm volatile("s_waitcnt vmcnt(" #n ")" ::: "memory")
; #define PG8_WAIT_L(n) asm volatile("s_waitcnt lgkmcnt(" #n ")" ::: "memory")
; #define PG8_BAR __builtin_amdgcn_s_barrier()
; #define PG8_SCHED __builtin_amdgcn_sched_barrier(0)
; #define PG8_MMA(ai, bj, At, Bt) do { __builtin_amdgcn_s_setprio(1); _Pragma("unroll") for (int m = 0; m < 4; ++m) _Pragma("unroll") for (int n = 0; n < 2; ++n) _Pragma("unroll") for (int k = 0; k < 2; ++k) \
;         acc[ai][bj][m][n] = __builtin_amdgcn_mfma_f32_16x16x32_bf16(Bt[n][k], At[m][k], acc[ai][bj][m][n], 0, 0, 0); __builtin_amdgcn_s_setprio(0); } while (0)
; #define PG8_WAIT_V(n) asm volatile("s_waitcnt vmcnt(" #n ")" ::: "memory")
; #define PG8_WAIT_L(n) asm volatile("s_waitcnt lgkmcnt(" #n ")" ::: "memory")
; #define PG8_BAR __builtin_amdgcn_s_barrier()
; #define PG8_SCHED __builtin_amdgcn_sched_barrier(0)
; template <class Epi, bool AFTER = false>
; __device__ __forceinline__ void gemm_phase(LAS unsigned char* lds, const Gemm g, const StaticOrder& S, const Epi& E) {
;     ...
;             PG8_BAR; PG8_WAIT_L(0); PG8_MMA(1, 0, At, B0); PG8_BAR; PG8_SCHED;
;             PG8_STAGE(PG8_SB(1, 1), b3 + hstep, voffB);
;             PG8_WAIT_V(6); PG8_BAR; PG8_MMA(1, 1, At, B1); PG8_BAR;
	s_waitcnt lgkmcnt(0)
	s_setprio 1
	s_waitcnt lgkmcnt(0)
	v_mfma_f32_16x16x32_bf16 v[108:111], v[198:201], v[166:169], v[108:111]
	v_mfma_f32_16x16x32_bf16 v[104:107], v[206:209], v[166:169], v[104:107]
	v_mfma_f32_16x16x32_bf16 v[92:95], v[198:201], v[174:177], v[92:95]
	v_mfma_f32_16x16x32_bf16 v[88:91], v[206:209], v[174:177], v[88:91]
	v_mfma_f32_16x16x32_bf16 v[76:79], v[198:201], v[182:185], v[76:79]
	v_mfma_f32_16x16x32_bf16 v[72:75], v[206:209], v[182:185], v[72:75]
	v_mfma_f32_16x16x32_bf16 v[68:71], v[198:201], v[190:193], v[68:71]
	v_mfma_f32_16x16x32_bf16 v[64:67], v[206:209], v[190:193], v[64:67]
	v_mfma_f32_16x16x32_bf16 v[108:111], v[202:205], v[170:173], v[108:111]
	v_mfma_f32_16x16x32_bf16 v[104:107], v[214:217], v[170:173], v[104:107]
	v_mfma_f32_16x16x32_bf16 v[92:95], v[202:205], v[178:181], v[92:95]
	v_mfma_f32_16x16x32_bf16 v[88:91], v[214:217], v[178:181], v[88:91]
	v_mfma_f32_16x16x32_bf16 v[76:79], v[202:205], v[186:189], v[76:79]
	v_mfma_f32_16x16x32_bf16 v[72:75], v[214:217], v[186:189], v[72:75]
	v_mfma_f32_16x16x32_bf16 v[68:71], v[202:205], v[194:197], v[68:71]
	v_mfma_f32_16x16x32_bf16 v[64:67], v[214:217], v[194:197], v[64:67]
	s_setprio 0
	s_mov_b32 m0, s46
	v_lshl_add_u64 v[210:211], v[220:221], 0, s[10:11]
	s_barrier
	ds_read_b128 v[166:169], v148 offset:49152
	ds_read_b128 v[170:173], v148 offset:50176
	ds_read_b128 v[174:177], v148 offset:51200
	ds_read_b128 v[178:181], v148 offset:52224
	ds_read_b128 v[182:185], v148 offset:53248
	ds_read_b128 v[186:189], v148 offset:54272
	ds_read_b128 v[190:193], v148 offset:55296
	ds_read_b128 v[194:197], v148 offset:56320
	global_load_lds_dwordx4 v[210:211], off
	v_lshl_add_u64 v[210:211], v[222:223], 0, s[10:11]
	s_mov_b32 m0, s47
	s_nop 0
	global_load_lds_dwordx4 v[210:211], off
	s_barrier
	s_waitcnt lgkmcnt(0)
	s_setprio 1
	s_waitcnt lgkmcnt(0)
	v_mfma_f32_16x16x32_bf16 v[60:63], v[150:153], v[166:169], v[60:63]
	v_mfma_f32_16x16x32_bf16 v[56:59], v[158:161], v[166:169], v[56:59]
	v_mfma_f32_16x16x32_bf16 v[52:55], v[150:153], v[174:177], v[52:55]
	v_mfma_f32_16x16x32_bf16 v[48:51], v[158:161], v[174:177], v[48:51]
	v_mfma_f32_16x16x32_bf16 v[40:43], v[150:153], v[182:185], v[40:43]
	v_mfma_f32_16x16x32_bf16 v[32:35], v[158:161], v[182:185], v[32:35]
	v_mfma_f32_16x16x32_bf16 v[24:27], v[150:153], v[190:193], v[24:27]
	v_mfma_f32_16x16x32_bf16 v[16:19], v[158:161], v[190:193], v[16:19]
	v_mfma_f32_16x16x32_bf16 v[60:63], v[154:157], v[170:173], v[60:63]
	v_mfma_f32_16x16x32_bf16 v[56:59], v[162:165], v[170:173], v[56:59]
	v_mfma_f32_16x16x32_bf16 v[52:55], v[154:157], v[178:181], v[52:55]
	v_mfma_f32_16x16x32_bf16 v[48:51], v[162:165], v[178:181], v[48:51]
	v_mfma_f32_16x16x32_bf16 v[40:43], v[154:157], v[186:189], v[40:43]
	v_mfma_f32_16x16x32_bf16 v[32:35], v[162:165], v[186:189], v[32:35]
	v_mfma_f32_16x16x32_bf16 v[24:27], v[154:157], v[194:197], v[24:27]
	v_mfma_f32_16x16x32_bf16 v[16:19], v[162:165], v[194:197], v[16:19]
	s_setprio 0
	s_barrier
	s_add_u32 s30, s30, 0x40080
	s_addc_u32 s31, s31, 0
	s_add_i32 s34, s34, s41
	v_lshl_add_u64 v[150:151], s[30:31], 0, v[130:131]
	s_mov_b32 m0, s34
	s_nop 0
	global_load_lds_dwordx4 v[150:151], off
	v_lshl_add_u64 v[150:151], s[30:31], 0, v[134:135]
	s_add_i32 m0, s34, 0x2000
	s_nop 0
	global_load_lds_dwordx4 v[150:151], off
	s_waitcnt vmcnt(6)
	global_load_dword v242, v240, s[98:99]
	v_add_u32_e32 v240, 0x10000, v240
	s_barrier
	s_setprio 1
	v_mfma_f32_16x16x32_bf16 v[44:47], v[198:201], v[166:169], v[44:47]
	v_mfma_f32_16x16x32_bf16 v[36:39], v[206:209], v[166:169], v[36:39]
	v_mfma_f32_16x16x32_bf16 v[28:31], v[198:201], v[174:177], v[28:31]
	v_mfma_f32_16x16x32_bf16 v[20:23], v[206:209], v[174:177], v[20:23]
	v_mfma_f32_16x16x32_bf16 v[12:15], v[198:201], v[182:185], v[12:15]
	v_mfma_f32_16x16x32_bf16 v[8:11], v[206:209], v[182:185], v[8:11]
	v_mfma_f32_16x16x32_bf16 v[4:7], v[198:201], v[190:193], v[4:7]
	v_mfma_f32_16x16x32_bf16 v[0:3], v[206:209], v[190:193], v[0:3]
	v_mfma_f32_16x16x32_bf16 v[44:47], v[202:205], v[170:173], v[44:47]
	v_mfma_f32_16x16x32_bf16 v[36:39], v[214:217], v[170:173], v[36:39]
	v_mfma_f32_16x16x32_bf16 v[28:31], v[202:205], v[178:181], v[28:31]
	v_mfma_f32_16x16x32_bf16 v[20:23], v[214:217], v[178:181], v[20:23]
	v_mfma_f32_16x16x32_bf16 v[12:15], v[202:205], v[186:189], v[12:15]
	v_mfma_f32_16x16x32_bf16 v[8:11], v[214:217], v[186:189], v[8:11]
	v_mfma_f32_16x16x32_bf16 v[4:7], v[202:205], v[194:197], v[4:7]
	v_mfma_f32_16x16x32_bf16 v[0:3], v[214:217], v[194:197], v[0:3]
	s_setprio 0
	s_add_i32 s60, s60, 2
	s_add_u32 s28, s28, 0x100
	s_addc_u32 s29, s29, 0
	s_add_u32 s58, s58, 0x100
	s_addc_u32 s59, s59, 0
	s_cmp_gt_u32 s60, 13
	s_nop 0
	s_nop 0
	s_nop 0
	s_barrier
